# v14 + phase-5 gate unit output stores widened to dwordx4 via permlane32_swap (4 stores per wave instead of 8)
# speedup vs baseline: 1.0021x; 1.0021x over previous
; #define GASP __attribute__((address_space(1)))
; __device__ __forceinline__ s16x4 vtr(const LAS unsigned char* p) { return __builtin_bit_cast(s16x4, __builtin_amdgcn_ds_read_tr16_b64_v4i16((LAS v4i16_t*)p)); }
; __device__ __forceinline__ bf16x8 cat8(s16x4 lo, s16x4 hi) { return (bf16x8){lo[0], lo[1], lo[2], lo[3], hi[0], hi[1], hi[2], hi[3]}; }
; __device__ __forceinline__ void gate_unit(const Params& p, LAS unsigned char* L, int row0, int n, int g, int sample_b) {
;     ...
;     if (active) {
;         const int i16 = lane & 15;
;         const int vlane_off = (8 * hi + (i16 >> 2)) * DA_VRS + (16 * ((lane >> 4) & 1) + 4 * (i16 & 3)) * 2 + dh * 128;
;         f32x16 OT[2];
; #pragma unroll
;         for (int e = 0; e < 2; ++e)
; #pragma unroll
;             for (int i = 0; i < 16; ++i) OT[e][i] = 0.f;
; #pragma unroll
;         for (int ks = 0; ks < 8; ++ks) if (ks < nks) {
; #pragma unroll
;             for (int db = 0; db < 2; ++db) {
;                 const s16x4 lo = vtr(L + vlane_off + (ks * 16) * DA_VRS + db * 64), hi4 = vtr(L + vlane_off + (ks * 16 + 4) * DA_VRS + db * 64);
;                 OT[db] = __builtin_amdgcn_mfma_f32_32x32x16_bf16(cat8(lo, hi4), wf[ks], OT[db], 0, 0, 0);
;             }
;         }
;         bf16_t* op = (bf16_t*)(ws + O_MIX) + (size_t)(row0 + te) * D + 512 + g * 128 + dh * 64 + 4 * hi;
; #pragma unroll
;         for (int db = 0; db < 2; ++db)
; #pragma unroll
;             for (int g4 = 0; g4 < 4; ++g4) { const u32x2 u2 = uu[db * 4 + g4];
;                 const float u0 = __uint_as_float(u2.x << 16), u1 = __uint_as_float(u2.x & 0xffff0000u), u2f = __uint_as_float(u2.y << 16), u3 = __uint_as_float(u2.y & 0xffff0000u);
;                 u32x2 w; w.x = pk2(u0 * (OT[db][4 * g4] + bias), u1 * (OT[db][4 * g4 + 1] + bias)); w.y = pk2(u2f * (OT[db][4 * g4 + 2] + bias), u3 * (OT[db][4 * g4 + 3] + bias));
;                 *(GASP u32x2*)(op + db * 32 + 8 * g4) = w; }
;     }
.LBB0_886:
	s_or_b64 exec, exec, s[10:11]
	s_and_b64 vcc, exec, s[6:7]
	s_waitcnt lgkmcnt(0)
	s_barrier
	s_cbranch_vccnz .LBB0_888
	v_lshrrev_b32_e32 v0, 2, v61
	s_waitcnt vmcnt(7)
	v_and_b32_e32 v2, 16, v61
	v_lshlrev_b32_e32 v3, 2, v61
	v_and_or_b32 v0, v0, 3, v76
	v_and_or_b32 v2, v3, 12, v2
	v_lshlrev_b32_e32 v2, 1, v2
	s_lshl_b32 s6, s13, 7
	v_mad_u32_u24 v0, v0, s88, 0
	v_add3_u32 v0, v0, v2, s6
	ds_read_b64_tr_b16 v[2:3], v0
	ds_read_b64_tr_b16 v[4:5], v0 offset:1280
	s_waitcnt vmcnt(6)
	ds_read_b64_tr_b16 v[8:9], v0 offset:1344
	ds_read_b64_tr_b16 v[6:7], v0 offset:64
	s_waitcnt vmcnt(0) lgkmcnt(2)
	v_mfma_f32_32x32x16_bf16 v[18:33], v[2:5], v[14:17], 0
	ds_read_b64_tr_b16 v[38:39], v0 offset:5120
	ds_read_b64_tr_b16 v[40:41], v0 offset:6400
	ds_read_b64_tr_b16 v[44:45], v0 offset:6464
	ds_read_b64_tr_b16 v[42:43], v0 offset:5184
	v_or_b32_e32 v0, s12, v88
	v_lshlrev_b32_e32 v0, 11, v0
	v_lshl_add_u64 v[46:47], s[22:23], 0, v[0:1]
	v_mov_b32_e32 v59, v1
	s_lshl_b32 s6, s13, 6
	s_ashr_i32 s7, s6, 31
	s_waitcnt lgkmcnt(4)
	v_mfma_f32_32x32x16_bf16 v[2:17], v[6:9], v[14:17], 0
	v_mov_b32_e32 v77, v1
	s_waitcnt lgkmcnt(2)
	v_mfma_f32_32x32x16_bf16 v[18:33], v[38:41], v[34:37], v[18:33]
	v_lshl_add_u64 v[38:39], v[58:59], 1, v[46:47]
	v_lshl_add_u64 v[38:39], s[6:7], 1, v[38:39]
	v_lshl_add_u64 v[38:39], v[38:39], 0, v[76:77]
	s_mov_b64 s[6:7], 0x2a9a1400
	s_waitcnt lgkmcnt(0)
	v_mfma_f32_32x32x16_bf16 v[2:17], v[42:45], v[34:37], v[2:17]
	v_lshlrev_b32_e32 v36, 16, v80
	v_and_b32_e32 v37, 0xffff0000, v80
	s_nop 3
	v_add_f32_e64 v18, v60, v18
	v_add_f32_e64 v19, v60, v19
	v_mul_f32_e64 v18, v18, v36
	v_mul_f32_e64 v19, v19, v37
	v_lshlrev_b32_e32 v36, 16, v81
	v_and_b32_e32 v37, 0xffff0000, v81
	v_pk_add_f32 v[20:21], v[60:61], v[20:21] op_sel_hi:[0,1]
	v_pk_mul_f32 v[20:21], v[20:21], v[36:37]
	v_cvt_pk_bf16_f32 v210, v18, v19
	v_cvt_pk_bf16_f32 v211, v20, v21
	v_add_co_u32_e32 v20, vcc, s89, v38
	v_lshl_add_u64 v[34:35], v[38:39], 0, s[6:7]
	v_mbcnt_lo_u32_b32 v218, -1, 0
	v_mbcnt_hi_u32_b32 v218, -1, v218
	v_and_b32_e32 v218, 32, v218
	v_lshrrev_b32_e32 v218, 2, v218
	v_mov_b32_e32 v219, 0
	v_lshl_add_u64 v[220:221], v[34:35], 0, v[218:219]
	s_nop 0
	v_addc_co_u32_e32 v21, vcc, 0, v39, vcc
	v_lshlrev_b32_e32 v18, 16, v78
	v_and_b32_e32 v19, 0xffff0000, v78
	v_pk_add_f32 v[20:21], v[60:61], v[22:23] op_sel_hi:[0,1]
	v_pk_mul_f32 v[18:19], v[20:21], v[18:19]
	v_lshlrev_b32_e32 v20, 16, v79
	v_and_b32_e32 v21, 0xffff0000, v79
	v_pk_add_f32 v[22:23], v[60:61], v[24:25] op_sel_hi:[0,1]
	v_pk_mul_f32 v[20:21], v[22:23], v[20:21]
	v_cvt_pk_bf16_f32 v212, v18, v19
	v_cvt_pk_bf16_f32 v213, v20, v21
	s_nop 1
	v_permlane32_swap_b32_e32 v210, v212
	v_permlane32_swap_b32_e32 v211, v213
	global_store_dwordx4 v[220:221], v[210:213], off
	v_lshlrev_b32_e32 v18, 16, v72
	v_and_b32_e32 v19, 0xffff0000, v72
	v_pk_add_f32 v[20:21], v[60:61], v[26:27] op_sel_hi:[0,1]
	v_pk_mul_f32 v[18:19], v[20:21], v[18:19]
	v_lshlrev_b32_e32 v20, 16, v73
	v_and_b32_e32 v21, 0xffff0000, v73
	v_pk_add_f32 v[22:23], v[60:61], v[28:29] op_sel_hi:[0,1]
	v_pk_mul_f32 v[20:21], v[22:23], v[20:21]
	v_cvt_pk_bf16_f32 v214, v18, v19
	v_cvt_pk_bf16_f32 v215, v20, v21
	v_lshlrev_b32_e32 v18, 16, v70
	v_and_b32_e32 v19, 0xffff0000, v70
	v_pk_add_f32 v[20:21], v[60:61], v[30:31] op_sel_hi:[0,1]
	v_pk_mul_f32 v[18:19], v[20:21], v[18:19]
	v_lshlrev_b32_e32 v20, 16, v71
	v_and_b32_e32 v21, 0xffff0000, v71
	v_pk_add_f32 v[22:23], v[60:61], v[32:33] op_sel_hi:[0,1]
	v_pk_mul_f32 v[20:21], v[22:23], v[20:21]
	v_cvt_pk_bf16_f32 v216, v18, v19
	v_cvt_pk_bf16_f32 v217, v20, v21
	s_nop 1
	v_permlane32_swap_b32_e32 v214, v216
	v_permlane32_swap_b32_e32 v215, v217
	global_store_dwordx4 v[220:221], v[214:217], off offset:32
	v_lshlrev_b32_e32 v18, 16, v68
	v_and_b32_e32 v19, 0xffff0000, v68
	v_pk_add_f32 v[2:3], v[60:61], v[2:3] op_sel_hi:[0,1]
	v_pk_mul_f32 v[2:3], v[2:3], v[18:19]
	v_lshlrev_b32_e32 v18, 16, v69
	v_and_b32_e32 v19, 0xffff0000, v69
	v_pk_add_f32 v[4:5], v[60:61], v[4:5] op_sel_hi:[0,1]
	v_pk_mul_f32 v[4:5], v[4:5], v[18:19]
	v_cvt_pk_bf16_f32 v210, v2, v3
	v_cvt_pk_bf16_f32 v211, v4, v5
	v_lshlrev_b32_e32 v2, 16, v66
	v_and_b32_e32 v3, 0xffff0000, v66
	v_pk_add_f32 v[4:5], v[60:61], v[6:7] op_sel_hi:[0,1]
	v_pk_mul_f32 v[2:3], v[4:5], v[2:3]
	v_lshlrev_b32_e32 v4, 16, v67
	v_and_b32_e32 v5, 0xffff0000, v67
	v_pk_add_f32 v[6:7], v[60:61], v[8:9] op_sel_hi:[0,1]
	v_pk_mul_f32 v[4:5], v[6:7], v[4:5]
	v_cvt_pk_bf16_f32 v212, v2, v3
	v_cvt_pk_bf16_f32 v213, v4, v5
	s_nop 1
	v_permlane32_swap_b32_e32 v210, v212
	v_permlane32_swap_b32_e32 v211, v213
	global_store_dwordx4 v[220:221], v[210:213], off offset:64
	v_lshlrev_b32_e32 v2, 16, v64
	v_and_b32_e32 v3, 0xffff0000, v64
	v_pk_add_f32 v[4:5], v[60:61], v[10:11] op_sel_hi:[0,1]
	v_pk_mul_f32 v[2:3], v[4:5], v[2:3]
	v_lshlrev_b32_e32 v4, 16, v65
	v_and_b32_e32 v5, 0xffff0000, v65
	v_pk_add_f32 v[6:7], v[60:61], v[12:13] op_sel_hi:[0,1]
	v_pk_mul_f32 v[4:5], v[6:7], v[4:5]
	v_cvt_pk_bf16_f32 v214, v2, v3
	v_cvt_pk_bf16_f32 v215, v4, v5
	v_lshlrev_b32_e32 v2, 16, v62
	v_and_b32_e32 v3, 0xffff0000, v62
	v_pk_add_f32 v[4:5], v[60:61], v[14:15] op_sel_hi:[0,1]
	v_pk_mul_f32 v[2:3], v[4:5], v[2:3]
	v_lshlrev_b32_e32 v4, 16, v63
	v_and_b32_e32 v5, 0xffff0000, v63
	v_pk_add_f32 v[6:7], v[60:61], v[16:17] op_sel_hi:[0,1]
	v_pk_mul_f32 v[4:5], v[6:7], v[4:5]
	v_cvt_pk_bf16_f32 v216, v2, v3
	v_cvt_pk_bf16_f32 v217, v4, v5
	s_nop 1
	v_permlane32_swap_b32_e32 v214, v216
	v_permlane32_swap_b32_e32 v215, v217
	global_store_dwordx4 v[220:221], v[214:217], off offset:96
